# EpiCmp epilogue: 4 bias quads loaded once (was 8x each behind vmcnt(0)), on top of v16
# speedup vs baseline: 1.0222x; 1.0038x over previous
; __device__ __forceinline__ unsigned cvt_pk_bf16(float lo, float hi) { unsigned r; asm volatile("v_cvt_pk_bf16_f32 %0, %1, %2" : "=v"(r) : "v"(lo), "v"(hi)); return r; }
; __device__ __forceinline__ float sigm(float x) { return __builtin_amdgcn_rcpf(1.0f + __builtin_amdgcn_exp2f(-1.4426950408889634f * x)); }
;     __device__ __forceinline__ void operator()(const f32x4 (&acc)[2][2][4][2], const Unit& u, int wr, int wc, int fr, int fq) const {
;         bf16_t* O = hid + (size_t)u.pn * 2048 * 256; const float* bb = bias + u.pn * 256;
;         const int row0 = u.pm * BM + wr * 64 + fr, col0 = wc * 32 + 8 * fq;
; #pragma unroll
;         for (int ai = 0; ai < 2; ++ai)
; #pragma unroll
;             for (int m = 0; m < 4; ++m) { const int row = row0 + ai * HALF + m * 16;
; #pragma unroll
;                 for (int bj = 0; bj < 2; ++bj) { const f32x4 b0 = *(const f32x4*)(bb + col0 + bj * HALF), b1 = *(const f32x4*)(bb + col0 + bj * HALF + 4);
;                     f32x4 v0 = acc[ai][bj][m][0] + b0, v1 = acc[ai][bj][m][1] + b1;
; #pragma unroll
;                     for (int e = 0; e < 4; ++e) { v0[e] = v0[e] * sigm(v0[e]); v1[e] = v1[e] * sigm(v1[e]); }
;                     u32x4 w; w.x = cvt_pk_bf16(v0[0], v0[1]); w.y = cvt_pk_bf16(v0[2], v0[3]); w.z = cvt_pk_bf16(v1[0], v1[1]); w.w = cvt_pk_bf16(v1[2], v1[3]);
;                     if (row < nvalid) *(u32x4*)(O + (size_t)row * 256 + col0 + bj * HALF) = w; } }
;     }
.LBB0_384:
	s_lshl_b32 s16, s14, 8
	s_ashr_i32 s17, s16, 31
	v_lshl_add_u64 v[150:151], s[16:17], 2, v[142:143]
	global_load_dwordx4 v[172:175], v[150:151], off
	global_load_dwordx4 v[176:179], v[150:151], off offset:16
	global_load_dwordx4 v[188:191], v[150:151], off offset:512
	global_load_dwordx4 v[192:195], v[150:151], off offset:528
	s_ashr_i32 s15, s14, 31
	v_lshl_add_u32 v152, s2, 8, v65
	s_lshl_b64 s[14:15], s[14:15], 20
	v_ashrrev_i32_e32 v153, 31, v152
	v_lshl_add_u64 v[154:155], v[144:145], 0, s[14:15]
	v_lshlrev_b64 v[156:157], 9, v[152:153]
	v_lshl_add_u64 v[156:157], v[154:155], 0, v[156:157]
	v_cmp_gt_i32_e32 vcc, s59, v152
	s_waitcnt vmcnt(0)
	v_pk_add_f32 v[134:135], v[134:135], v[174:175]
	v_pk_add_f32 v[132:133], v[132:133], v[172:173]
	v_pk_add_f32 v[130:131], v[130:131], v[178:179]
	v_pk_add_f32 v[128:129], v[128:129], v[176:177]
	v_mul_f32_e32 v160, 0xbfb8aa3b, v132
	v_mul_f32_e32 v161, 0xbfb8aa3b, v128
	v_mul_f32_e32 v162, 0xbfb8aa3b, v133
	v_mul_f32_e32 v163, 0xbfb8aa3b, v129
	v_mul_f32_e32 v164, 0xbfb8aa3b, v134
	v_mul_f32_e32 v165, 0xbfb8aa3b, v130
	v_mul_f32_e32 v166, 0xbfb8aa3b, v135
	v_mul_f32_e32 v167, 0xbfb8aa3b, v131
	v_exp_f32_e32 v160, v160
	v_exp_f32_e32 v161, v161
	v_exp_f32_e32 v162, v162
	v_exp_f32_e32 v163, v163
	v_exp_f32_e32 v164, v164
	v_exp_f32_e32 v165, v165
	v_exp_f32_e32 v166, v166
	v_exp_f32_e32 v167, v167
	v_add_f32_e32 v160, 1.0, v160
	v_add_f32_e32 v161, 1.0, v161
	v_add_f32_e32 v162, 1.0, v162
	v_add_f32_e32 v163, 1.0, v163
	v_add_f32_e32 v164, 1.0, v164
	v_add_f32_e32 v165, 1.0, v165
	v_add_f32_e32 v166, 1.0, v166
	v_add_f32_e32 v167, 1.0, v167
	v_rcp_f32_e32 v160, v160
	v_rcp_f32_e32 v161, v161
	v_rcp_f32_e32 v162, v162
	v_rcp_f32_e32 v163, v163
	v_rcp_f32_e32 v164, v164
	v_rcp_f32_e32 v165, v165
	v_rcp_f32_e32 v166, v166
	v_rcp_f32_e32 v167, v167
	v_mul_f32_e32 v132, v132, v160
	v_mul_f32_e32 v160, v128, v161
	v_mul_f32_e32 v128, v133, v162
	v_mul_f32_e32 v133, v129, v163
	v_mul_f32_e32 v129, v134, v164
	v_mul_f32_e32 v134, v130, v165
	v_mul_f32_e32 v130, v135, v166
	v_mul_f32_e32 v131, v131, v167
	v_cvt_pk_bf16_f32 v128, v132, v128
	v_cvt_pk_bf16_f32 v129, v129, v130
	v_cvt_pk_bf16_f32 v130, v160, v133
	v_cvt_pk_bf16_f32 v131, v134, v131
	s_and_saveexec_b64 s[14:15], vcc
	s_cbranch_execz .LBB0_386
	global_store_dwordx4 v[156:157], v[128:131], off
.LBB0_386:
	s_or_b64 exec, exec, s[14:15]
	s_nop 1
	v_pk_add_f32 v[126:127], v[126:127], v[190:191]
	v_pk_add_f32 v[124:125], v[124:125], v[188:189]
	v_pk_add_f32 v[122:123], v[122:123], v[194:195]
	v_pk_add_f32 v[120:121], v[120:121], v[192:193]
	v_mul_f32_e32 v128, 0xbfb8aa3b, v124
	v_mul_f32_e32 v129, 0xbfb8aa3b, v120
	v_mul_f32_e32 v130, 0xbfb8aa3b, v125
	v_mul_f32_e32 v131, 0xbfb8aa3b, v121
	v_mul_f32_e32 v132, 0xbfb8aa3b, v126
	v_mul_f32_e32 v133, 0xbfb8aa3b, v122
	v_mul_f32_e32 v134, 0xbfb8aa3b, v127
	v_mul_f32_e32 v135, 0xbfb8aa3b, v123
	v_exp_f32_e32 v128, v128
	v_exp_f32_e32 v129, v129
	v_exp_f32_e32 v130, v130
	v_exp_f32_e32 v131, v131
	v_exp_f32_e32 v132, v132
	v_exp_f32_e32 v133, v133
	v_exp_f32_e32 v134, v134
	v_exp_f32_e32 v135, v135
	v_add_f32_e32 v128, 1.0, v128
	v_add_f32_e32 v129, 1.0, v129
	v_add_f32_e32 v130, 1.0, v130
	v_add_f32_e32 v131, 1.0, v131
	v_add_f32_e32 v132, 1.0, v132
	v_add_f32_e32 v133, 1.0, v133
	v_add_f32_e32 v134, 1.0, v134
	v_add_f32_e32 v135, 1.0, v135
	v_rcp_f32_e32 v128, v128
	v_rcp_f32_e32 v129, v129
	v_rcp_f32_e32 v130, v130
	v_rcp_f32_e32 v131, v131
	v_rcp_f32_e32 v132, v132
	v_rcp_f32_e32 v133, v133
	v_rcp_f32_e32 v134, v134
	v_rcp_f32_e32 v135, v135
	v_mul_f32_e32 v124, v124, v128
	v_mul_f32_e32 v128, v120, v129
	v_mul_f32_e32 v120, v125, v130
	v_mul_f32_e32 v125, v121, v131
	v_mul_f32_e32 v121, v126, v132
	v_mul_f32_e32 v126, v122, v133
	v_mul_f32_e32 v122, v127, v134
	v_mul_f32_e32 v123, v123, v135
	v_cvt_pk_bf16_f32 v120, v124, v120
	v_cvt_pk_bf16_f32 v121, v121, v122
	v_cvt_pk_bf16_f32 v122, v128, v125
	v_cvt_pk_bf16_f32 v123, v126, v123
	s_and_saveexec_b64 s[14:15], vcc
	s_cbranch_execz .LBB0_388
	global_store_dwordx4 v[156:157], v[120:123], off offset:256
.LBB0_388:
	s_or_b64 exec, exec, s[14:15]
	s_nop 1
	v_or_b32_e32 v130, 16, v152
	v_ashrrev_i32_e32 v131, 31, v130
	v_lshlrev_b64 v[120:121], 9, v[130:131]
	v_lshl_add_u64 v[120:121], v[154:155], 0, v[120:121]
	v_cmp_gt_i32_e32 vcc, s59, v130
	v_pk_add_f32 v[118:119], v[118:119], v[174:175]
	v_pk_add_f32 v[116:117], v[116:117], v[172:173]
	v_pk_add_f32 v[114:115], v[114:115], v[178:179]
	v_pk_add_f32 v[112:113], v[112:113], v[176:177]
	v_mul_f32_e32 v122, 0xbfb8aa3b, v116
	v_mul_f32_e32 v123, 0xbfb8aa3b, v112
	v_mul_f32_e32 v124, 0xbfb8aa3b, v117
	v_mul_f32_e32 v125, 0xbfb8aa3b, v113
	v_mul_f32_e32 v126, 0xbfb8aa3b, v118
	v_mul_f32_e32 v127, 0xbfb8aa3b, v114
	v_mul_f32_e32 v128, 0xbfb8aa3b, v119
	v_mul_f32_e32 v129, 0xbfb8aa3b, v115
	v_exp_f32_e32 v122, v122
	v_exp_f32_e32 v123, v123
	v_exp_f32_e32 v124, v124
	v_exp_f32_e32 v125, v125
	v_exp_f32_e32 v126, v126
	v_exp_f32_e32 v127, v127
	v_exp_f32_e32 v128, v128
	v_exp_f32_e32 v129, v129
	v_add_f32_e32 v122, 1.0, v122
	v_add_f32_e32 v123, 1.0, v123
	v_add_f32_e32 v124, 1.0, v124
	v_add_f32_e32 v125, 1.0, v125
	v_add_f32_e32 v126, 1.0, v126
	v_add_f32_e32 v127, 1.0, v127
	v_add_f32_e32 v128, 1.0, v128
	v_add_f32_e32 v129, 1.0, v129
	v_rcp_f32_e32 v122, v122
	v_rcp_f32_e32 v123, v123
	v_rcp_f32_e32 v124, v124
	v_rcp_f32_e32 v125, v125
	v_rcp_f32_e32 v126, v126
	v_rcp_f32_e32 v127, v127
	v_rcp_f32_e32 v128, v128
	v_rcp_f32_e32 v129, v129
	v_mul_f32_e32 v116, v116, v122
	v_mul_f32_e32 v122, v112, v123
	v_mul_f32_e32 v112, v117, v124
	v_mul_f32_e32 v117, v113, v125
	v_mul_f32_e32 v113, v118, v126
	v_mul_f32_e32 v118, v114, v127
	v_mul_f32_e32 v114, v119, v128
	v_mul_f32_e32 v115, v115, v129
	v_cvt_pk_bf16_f32 v112, v116, v112
	v_cvt_pk_bf16_f32 v113, v113, v114
	v_cvt_pk_bf16_f32 v114, v122, v117
	v_cvt_pk_bf16_f32 v115, v118, v115
	s_and_saveexec_b64 s[14:15], vcc
	s_cbranch_execz .LBB0_390
	global_store_dwordx4 v[120:121], v[112:115], off
; __device__ __forceinline__ unsigned cvt_pk_bf16(float lo, float hi) { unsigned r; asm volatile("v_cvt_pk_bf16_f32 %0, %1, %2" : "=v"(r) : "v"(lo), "v"(hi)); return r; }
; __device__ __forceinline__ float sigm(float x) { return __builtin_amdgcn_rcpf(1.0f + __builtin_amdgcn_exp2f(-1.4426950408889634f * x)); }
;     __device__ __forceinline__ void operator()(const f32x4 (&acc)[2][2][4][2], const Unit& u, int wr, int wc, int fr, int fq) const {
;     ...
;             for (int m = 0; m < 4; ++m) { const int row = row0 + ai * HALF + m * 16;
; #pragma unroll
;                 for (int bj = 0; bj < 2; ++bj) { const f32x4 b0 = *(const f32x4*)(bb + col0 + bj * HALF), b1 = *(const f32x4*)(bb + col0 + bj * HALF + 4);
;                     f32x4 v0 = acc[ai][bj][m][0] + b0, v1 = acc[ai][bj][m][1] + b1;
; #pragma unroll
;                     for (int e = 0; e < 4; ++e) { v0[e] = v0[e] * sigm(v0[e]); v1[e] = v1[e] * sigm(v1[e]); }
;                     u32x4 w; w.x = cvt_pk_bf16(v0[0], v0[1]); w.y = cvt_pk_bf16(v0[2], v0[3]); w.z = cvt_pk_bf16(v1[0], v1[1]); w.w = cvt_pk_bf16(v1[2], v1[3]);
;                     if (row < nvalid) *(u32x4*)(O + (size_t)row * 256 + col0 + bj * HALF) = w; } }
.LBB0_390:
	s_or_b64 exec, exec, s[14:15]
	s_nop 1
	v_pk_add_f32 v[110:111], v[110:111], v[190:191]
	v_pk_add_f32 v[108:109], v[108:109], v[188:189]
	v_pk_add_f32 v[106:107], v[106:107], v[194:195]
	v_pk_add_f32 v[104:105], v[104:105], v[192:193]
	v_mul_f32_e32 v112, 0xbfb8aa3b, v108
	v_mul_f32_e32 v113, 0xbfb8aa3b, v104
	v_mul_f32_e32 v114, 0xbfb8aa3b, v109
	v_mul_f32_e32 v115, 0xbfb8aa3b, v105
	v_mul_f32_e32 v116, 0xbfb8aa3b, v110
	v_mul_f32_e32 v117, 0xbfb8aa3b, v106
	v_mul_f32_e32 v118, 0xbfb8aa3b, v111
	v_mul_f32_e32 v119, 0xbfb8aa3b, v107
	v_exp_f32_e32 v112, v112
	v_exp_f32_e32 v113, v113
	v_exp_f32_e32 v114, v114
	v_exp_f32_e32 v115, v115
	v_exp_f32_e32 v116, v116
	v_exp_f32_e32 v117, v117
	v_exp_f32_e32 v118, v118
	v_exp_f32_e32 v119, v119
	v_add_f32_e32 v112, 1.0, v112
	v_add_f32_e32 v113, 1.0, v113
	v_add_f32_e32 v114, 1.0, v114
	v_add_f32_e32 v115, 1.0, v115
	v_add_f32_e32 v116, 1.0, v116
	v_add_f32_e32 v117, 1.0, v117
	v_add_f32_e32 v118, 1.0, v118
	v_add_f32_e32 v119, 1.0, v119
	v_rcp_f32_e32 v112, v112
	v_rcp_f32_e32 v113, v113
	v_rcp_f32_e32 v114, v114
	v_rcp_f32_e32 v115, v115
	v_rcp_f32_e32 v116, v116
	v_rcp_f32_e32 v117, v117
	v_rcp_f32_e32 v118, v118
	v_rcp_f32_e32 v119, v119
	v_mul_f32_e32 v108, v108, v112
	v_mul_f32_e32 v112, v104, v113
	v_mul_f32_e32 v104, v109, v114
	v_mul_f32_e32 v109, v105, v115
	v_mul_f32_e32 v105, v110, v116
	v_mul_f32_e32 v110, v106, v117
	v_mul_f32_e32 v106, v111, v118
	v_mul_f32_e32 v107, v107, v119
	v_cvt_pk_bf16_f32 v104, v108, v104
	v_cvt_pk_bf16_f32 v105, v105, v106
	v_cvt_pk_bf16_f32 v106, v112, v109
	v_cvt_pk_bf16_f32 v107, v110, v107
	s_and_saveexec_b64 s[14:15], vcc
	s_cbranch_execz .LBB0_392
	global_store_dwordx4 v[120:121], v[104:107], off offset:256
.LBB0_392:
	s_or_b64 exec, exec, s[14:15]
	s_nop 1
	v_or_b32_e32 v114, 32, v152
	v_ashrrev_i32_e32 v115, 31, v114
	v_lshlrev_b64 v[104:105], 9, v[114:115]
	v_lshl_add_u64 v[104:105], v[154:155], 0, v[104:105]
	v_cmp_gt_i32_e32 vcc, s59, v114
	v_pk_add_f32 v[102:103], v[102:103], v[174:175]
	v_pk_add_f32 v[100:101], v[100:101], v[172:173]
	v_pk_add_f32 v[98:99], v[98:99], v[178:179]
	v_pk_add_f32 v[96:97], v[96:97], v[176:177]
	v_mul_f32_e32 v106, 0xbfb8aa3b, v100
	v_mul_f32_e32 v107, 0xbfb8aa3b, v96
	v_mul_f32_e32 v108, 0xbfb8aa3b, v101
	v_mul_f32_e32 v109, 0xbfb8aa3b, v97
	v_mul_f32_e32 v110, 0xbfb8aa3b, v102
	v_mul_f32_e32 v111, 0xbfb8aa3b, v98
	v_mul_f32_e32 v112, 0xbfb8aa3b, v103
	v_mul_f32_e32 v113, 0xbfb8aa3b, v99
	v_exp_f32_e32 v106, v106
	v_exp_f32_e32 v107, v107
	v_exp_f32_e32 v108, v108
	v_exp_f32_e32 v109, v109
	v_exp_f32_e32 v110, v110
	v_exp_f32_e32 v111, v111
	v_exp_f32_e32 v112, v112
	v_exp_f32_e32 v113, v113
	v_add_f32_e32 v106, 1.0, v106
	v_add_f32_e32 v107, 1.0, v107
	v_add_f32_e32 v108, 1.0, v108
	v_add_f32_e32 v109, 1.0, v109
	v_add_f32_e32 v110, 1.0, v110
	v_add_f32_e32 v111, 1.0, v111
	v_add_f32_e32 v112, 1.0, v112
	v_add_f32_e32 v113, 1.0, v113
	v_rcp_f32_e32 v106, v106
	v_rcp_f32_e32 v107, v107
	v_rcp_f32_e32 v108, v108
	v_rcp_f32_e32 v109, v109
	v_rcp_f32_e32 v110, v110
	v_rcp_f32_e32 v111, v111
	v_rcp_f32_e32 v112, v112
	v_rcp_f32_e32 v113, v113
	v_mul_f32_e32 v100, v100, v106
	v_mul_f32_e32 v106, v96, v107
	v_mul_f32_e32 v96, v101, v108
	v_mul_f32_e32 v101, v97, v109
	v_mul_f32_e32 v97, v102, v110
	v_mul_f32_e32 v102, v98, v111
	v_mul_f32_e32 v98, v103, v112
	v_mul_f32_e32 v99, v99, v113
	v_cvt_pk_bf16_f32 v96, v100, v96
	v_cvt_pk_bf16_f32 v97, v97, v98
	v_cvt_pk_bf16_f32 v98, v106, v101
	v_cvt_pk_bf16_f32 v99, v102, v99
	s_and_saveexec_b64 s[14:15], vcc
	s_cbranch_execz .LBB0_394
	global_store_dwordx4 v[104:105], v[96:99], off
.LBB0_394:
	s_or_b64 exec, exec, s[14:15]
	s_nop 1
	v_pk_add_f32 v[94:95], v[94:95], v[190:191]
	v_pk_add_f32 v[92:93], v[92:93], v[188:189]
	v_pk_add_f32 v[90:91], v[90:91], v[194:195]
	v_pk_add_f32 v[88:89], v[88:89], v[192:193]
	v_mul_f32_e32 v96, 0xbfb8aa3b, v92
	v_mul_f32_e32 v97, 0xbfb8aa3b, v88
	v_mul_f32_e32 v98, 0xbfb8aa3b, v93
	v_mul_f32_e32 v99, 0xbfb8aa3b, v89
	v_mul_f32_e32 v100, 0xbfb8aa3b, v94
	v_mul_f32_e32 v101, 0xbfb8aa3b, v90
	v_mul_f32_e32 v102, 0xbfb8aa3b, v95
	v_mul_f32_e32 v103, 0xbfb8aa3b, v91
	v_exp_f32_e32 v96, v96
	v_exp_f32_e32 v97, v97
	v_exp_f32_e32 v98, v98
	v_exp_f32_e32 v99, v99
	v_exp_f32_e32 v100, v100
	v_exp_f32_e32 v101, v101
	v_exp_f32_e32 v102, v102
	v_exp_f32_e32 v103, v103
	v_add_f32_e32 v96, 1.0, v96
	v_add_f32_e32 v97, 1.0, v97
	v_add_f32_e32 v98, 1.0, v98
	v_add_f32_e32 v99, 1.0, v99
	v_add_f32_e32 v100, 1.0, v100
	v_add_f32_e32 v101, 1.0, v101
	v_add_f32_e32 v102, 1.0, v102
	v_add_f32_e32 v103, 1.0, v103
	v_rcp_f32_e32 v96, v96
	v_rcp_f32_e32 v97, v97
	v_rcp_f32_e32 v98, v98
	v_rcp_f32_e32 v99, v99
	v_rcp_f32_e32 v100, v100
	v_rcp_f32_e32 v101, v101
	v_rcp_f32_e32 v102, v102
	v_rcp_f32_e32 v103, v103
	v_mul_f32_e32 v92, v92, v96
	v_mul_f32_e32 v96, v88, v97
	v_mul_f32_e32 v88, v93, v98
	v_mul_f32_e32 v93, v89, v99
	v_mul_f32_e32 v89, v94, v100
	v_mul_f32_e32 v94, v90, v101
	v_mul_f32_e32 v90, v95, v102
	v_mul_f32_e32 v91, v91, v103
	v_cvt_pk_bf16_f32 v88, v92, v88
	v_cvt_pk_bf16_f32 v89, v89, v90
	v_cvt_pk_bf16_f32 v90, v96, v93
	v_cvt_pk_bf16_f32 v91, v94, v91
	s_and_saveexec_b64 s[14:15], vcc
	s_cbranch_execz .LBB0_396
	global_store_dwordx4 v[104:105], v[88:91], off offset:256
; __device__ __forceinline__ unsigned cvt_pk_bf16(float lo, float hi) { unsigned r; asm volatile("v_cvt_pk_bf16_f32 %0, %1, %2" : "=v"(r) : "v"(lo), "v"(hi)); return r; }
; __device__ __forceinline__ float sigm(float x) { return __builtin_amdgcn_rcpf(1.0f + __builtin_amdgcn_exp2f(-1.4426950408889634f * x)); }
;     __device__ __forceinline__ void operator()(const f32x4 (&acc)[2][2][4][2], const Unit& u, int wr, int wc, int fr, int fq) const {
;     ...
;             for (int m = 0; m < 4; ++m) { const int row = row0 + ai * HALF + m * 16;
; #pragma unroll
;                 for (int bj = 0; bj < 2; ++bj) { const f32x4 b0 = *(const f32x4*)(bb + col0 + bj * HALF), b1 = *(const f32x4*)(bb + col0 + bj * HALF + 4);
;                     f32x4 v0 = acc[ai][bj][m][0] + b0, v1 = acc[ai][bj][m][1] + b1;
; #pragma unroll
;                     for (int e = 0; e < 4; ++e) { v0[e] = v0[e] * sigm(v0[e]); v1[e] = v1[e] * sigm(v1[e]); }
;                     u32x4 w; w.x = cvt_pk_bf16(v0[0], v0[1]); w.y = cvt_pk_bf16(v0[2], v0[3]); w.z = cvt_pk_bf16(v1[0], v1[1]); w.w = cvt_pk_bf16(v1[2], v1[3]);
;                     if (row < nvalid) *(u32x4*)(O + (size_t)row * 256 + col0 + bj * HALF) = w; } }
.LBB0_396:
	s_or_b64 exec, exec, s[14:15]
	s_nop 1
	v_or_b32_e32 v98, 48, v152
	v_ashrrev_i32_e32 v99, 31, v98
	v_lshlrev_b64 v[88:89], 9, v[98:99]
	v_lshl_add_u64 v[88:89], v[154:155], 0, v[88:89]
	v_cmp_gt_i32_e32 vcc, s59, v98
	v_pk_add_f32 v[86:87], v[86:87], v[174:175]
	v_pk_add_f32 v[84:85], v[84:85], v[172:173]
	v_pk_add_f32 v[82:83], v[82:83], v[178:179]
	v_pk_add_f32 v[80:81], v[80:81], v[176:177]
	v_mul_f32_e32 v90, 0xbfb8aa3b, v84
	v_mul_f32_e32 v91, 0xbfb8aa3b, v80
	v_mul_f32_e32 v92, 0xbfb8aa3b, v85
	v_mul_f32_e32 v93, 0xbfb8aa3b, v81
	v_mul_f32_e32 v94, 0xbfb8aa3b, v86
	v_mul_f32_e32 v95, 0xbfb8aa3b, v82
	v_mul_f32_e32 v96, 0xbfb8aa3b, v87
	v_mul_f32_e32 v97, 0xbfb8aa3b, v83
	v_exp_f32_e32 v90, v90
	v_exp_f32_e32 v91, v91
	v_exp_f32_e32 v92, v92
	v_exp_f32_e32 v93, v93
	v_exp_f32_e32 v94, v94
	v_exp_f32_e32 v95, v95
	v_exp_f32_e32 v96, v96
	v_exp_f32_e32 v97, v97
	v_add_f32_e32 v90, 1.0, v90
	v_add_f32_e32 v91, 1.0, v91
	v_add_f32_e32 v92, 1.0, v92
	v_add_f32_e32 v93, 1.0, v93
	v_add_f32_e32 v94, 1.0, v94
	v_add_f32_e32 v95, 1.0, v95
	v_add_f32_e32 v96, 1.0, v96
	v_add_f32_e32 v97, 1.0, v97
	v_rcp_f32_e32 v90, v90
	v_rcp_f32_e32 v91, v91
	v_rcp_f32_e32 v92, v92
	v_rcp_f32_e32 v93, v93
	v_rcp_f32_e32 v94, v94
	v_rcp_f32_e32 v95, v95
	v_rcp_f32_e32 v96, v96
	v_rcp_f32_e32 v97, v97
	v_mul_f32_e32 v84, v84, v90
	v_mul_f32_e32 v90, v80, v91
	v_mul_f32_e32 v80, v85, v92
	v_mul_f32_e32 v85, v81, v93
	v_mul_f32_e32 v81, v86, v94
	v_mul_f32_e32 v86, v82, v95
	v_mul_f32_e32 v82, v87, v96
	v_mul_f32_e32 v83, v83, v97
	v_cvt_pk_bf16_f32 v80, v84, v80
	v_cvt_pk_bf16_f32 v81, v81, v82
	v_cvt_pk_bf16_f32 v82, v90, v85
	v_cvt_pk_bf16_f32 v83, v86, v83
	s_and_saveexec_b64 s[14:15], vcc
	s_cbranch_execz .LBB0_398
	global_store_dwordx4 v[88:89], v[80:83], off
.LBB0_398:
	s_or_b64 exec, exec, s[14:15]
	s_nop 1
	v_pk_add_f32 v[78:79], v[78:79], v[190:191]
	v_pk_add_f32 v[76:77], v[76:77], v[188:189]
	v_pk_add_f32 v[74:75], v[74:75], v[194:195]
	v_pk_add_f32 v[72:73], v[72:73], v[192:193]
	v_mul_f32_e32 v80, 0xbfb8aa3b, v76
	v_mul_f32_e32 v81, 0xbfb8aa3b, v72
	v_mul_f32_e32 v82, 0xbfb8aa3b, v77
	v_mul_f32_e32 v83, 0xbfb8aa3b, v73
	v_mul_f32_e32 v84, 0xbfb8aa3b, v78
	v_mul_f32_e32 v85, 0xbfb8aa3b, v74
	v_mul_f32_e32 v86, 0xbfb8aa3b, v79
	v_mul_f32_e32 v87, 0xbfb8aa3b, v75
	v_exp_f32_e32 v80, v80
	v_exp_f32_e32 v81, v81
	v_exp_f32_e32 v82, v82
	v_exp_f32_e32 v83, v83
	v_exp_f32_e32 v84, v84
	v_exp_f32_e32 v85, v85
	v_exp_f32_e32 v86, v86
	v_exp_f32_e32 v87, v87
	v_add_f32_e32 v80, 1.0, v80
	v_add_f32_e32 v81, 1.0, v81
	v_add_f32_e32 v82, 1.0, v82
	v_add_f32_e32 v83, 1.0, v83
	v_add_f32_e32 v84, 1.0, v84
	v_add_f32_e32 v85, 1.0, v85
	v_add_f32_e32 v86, 1.0, v86
	v_add_f32_e32 v87, 1.0, v87
	v_rcp_f32_e32 v80, v80
	v_rcp_f32_e32 v81, v81
	v_rcp_f32_e32 v82, v82
	v_rcp_f32_e32 v83, v83
	v_rcp_f32_e32 v84, v84
	v_rcp_f32_e32 v85, v85
	v_rcp_f32_e32 v86, v86
	v_rcp_f32_e32 v87, v87
	v_mul_f32_e32 v76, v76, v80
	v_mul_f32_e32 v80, v72, v81
	v_mul_f32_e32 v72, v77, v82
	v_mul_f32_e32 v77, v73, v83
	v_mul_f32_e32 v73, v78, v84
	v_mul_f32_e32 v78, v74, v85
	v_mul_f32_e32 v74, v79, v86
	v_mul_f32_e32 v75, v75, v87
	v_cvt_pk_bf16_f32 v72, v76, v72
	v_cvt_pk_bf16_f32 v73, v73, v74
	v_cvt_pk_bf16_f32 v74, v80, v77
	v_cvt_pk_bf16_f32 v75, v78, v75
	s_and_saveexec_b64 s[14:15], vcc
	s_cbranch_execz .LBB0_400
	global_store_dwordx4 v[88:89], v[72:75], off offset:256
.LBB0_400:
	s_or_b64 exec, exec, s[14:15]
	s_nop 1
	v_lshlrev_b64 v[72:73], 9, v[152:153]
	v_lshl_add_u64 v[72:73], v[154:155], 0, v[72:73]
	s_mov_b64 s[14:15], 0x10000
	s_movk_i32 s2, 0x77c
	v_lshl_add_u64 v[72:73], v[72:73], 0, s[14:15]
	v_cmp_gt_i32_e32 vcc, s2, v152
	v_pk_add_f32 v[62:63], v[62:63], v[174:175]
	v_pk_add_f32 v[60:61], v[60:61], v[172:173]
	v_pk_add_f32 v[58:59], v[58:59], v[178:179]
	v_pk_add_f32 v[56:57], v[56:57], v[176:177]
	v_mul_f32_e32 v74, 0xbfb8aa3b, v60
	v_mul_f32_e32 v75, 0xbfb8aa3b, v56
	v_mul_f32_e32 v76, 0xbfb8aa3b, v61
	v_mul_f32_e32 v77, 0xbfb8aa3b, v57
	v_mul_f32_e32 v78, 0xbfb8aa3b, v62
	v_mul_f32_e32 v79, 0xbfb8aa3b, v58
	v_mul_f32_e32 v80, 0xbfb8aa3b, v63
	v_mul_f32_e32 v81, 0xbfb8aa3b, v59
	v_exp_f32_e32 v74, v74
	v_exp_f32_e32 v75, v75
	v_exp_f32_e32 v76, v76
	v_exp_f32_e32 v77, v77
	v_exp_f32_e32 v78, v78
	v_exp_f32_e32 v79, v79
	v_exp_f32_e32 v80, v80
	v_exp_f32_e32 v81, v81
	v_add_f32_e32 v74, 1.0, v74
	v_add_f32_e32 v75, 1.0, v75
	v_add_f32_e32 v76, 1.0, v76
	v_add_f32_e32 v77, 1.0, v77
	v_add_f32_e32 v78, 1.0, v78
	v_add_f32_e32 v79, 1.0, v79
	v_add_f32_e32 v80, 1.0, v80
	v_add_f32_e32 v81, 1.0, v81
	v_rcp_f32_e32 v74, v74
	v_rcp_f32_e32 v75, v75
	v_rcp_f32_e32 v76, v76
	v_rcp_f32_e32 v77, v77
	v_rcp_f32_e32 v78, v78
	v_rcp_f32_e32 v79, v79
	v_rcp_f32_e32 v80, v80
	v_rcp_f32_e32 v81, v81
	v_mul_f32_e32 v60, v60, v74
	v_mul_f32_e32 v74, v56, v75
	v_mul_f32_e32 v56, v61, v76
	v_mul_f32_e32 v61, v57, v77
	v_mul_f32_e32 v57, v62, v78
	v_mul_f32_e32 v62, v58, v79
	v_mul_f32_e32 v58, v63, v80
	v_mul_f32_e32 v59, v59, v81
	v_cvt_pk_bf16_f32 v56, v60, v56
	v_cvt_pk_bf16_f32 v57, v57, v58
	v_cvt_pk_bf16_f32 v58, v74, v61
	v_cvt_pk_bf16_f32 v59, v62, v59
	s_and_saveexec_b64 s[14:15], vcc
	s_cbranch_execz .LBB0_402
	global_store_dwordx4 v[72:73], v[56:59], off
; __device__ __forceinline__ unsigned cvt_pk_bf16(float lo, float hi) { unsigned r; asm volatile("v_cvt_pk_bf16_f32 %0, %1, %2" : "=v"(r) : "v"(lo), "v"(hi)); return r; }
; __device__ __forceinline__ float sigm(float x) { return __builtin_amdgcn_rcpf(1.0f + __builtin_amdgcn_exp2f(-1.4426950408889634f * x)); }
;     __device__ __forceinline__ void operator()(const f32x4 (&acc)[2][2][4][2], const Unit& u, int wr, int wc, int fr, int fq) const {
;     ...
;             for (int m = 0; m < 4; ++m) { const int row = row0 + ai * HALF + m * 16;
; #pragma unroll
;                 for (int bj = 0; bj < 2; ++bj) { const f32x4 b0 = *(const f32x4*)(bb + col0 + bj * HALF), b1 = *(const f32x4*)(bb + col0 + bj * HALF + 4);
;                     f32x4 v0 = acc[ai][bj][m][0] + b0, v1 = acc[ai][bj][m][1] + b1;
; #pragma unroll
;                     for (int e = 0; e < 4; ++e) { v0[e] = v0[e] * sigm(v0[e]); v1[e] = v1[e] * sigm(v1[e]); }
;                     u32x4 w; w.x = cvt_pk_bf16(v0[0], v0[1]); w.y = cvt_pk_bf16(v0[2], v0[3]); w.z = cvt_pk_bf16(v1[0], v1[1]); w.w = cvt_pk_bf16(v1[2], v1[3]);
;                     if (row < nvalid) *(u32x4*)(O + (size_t)row * 256 + col0 + bj * HALF) = w; } }
.LBB0_402:
	s_or_b64 exec, exec, s[14:15]
	s_nop 1
	v_pk_add_f32 v[54:55], v[54:55], v[190:191]
	v_pk_add_f32 v[52:53], v[52:53], v[188:189]
	v_pk_add_f32 v[50:51], v[50:51], v[194:195]
	v_pk_add_f32 v[48:49], v[48:49], v[192:193]
	v_mul_f32_e32 v56, 0xbfb8aa3b, v52
	v_mul_f32_e32 v57, 0xbfb8aa3b, v48
	v_mul_f32_e32 v58, 0xbfb8aa3b, v53
	v_mul_f32_e32 v59, 0xbfb8aa3b, v49
	v_mul_f32_e32 v60, 0xbfb8aa3b, v54
	v_mul_f32_e32 v61, 0xbfb8aa3b, v50
	v_mul_f32_e32 v62, 0xbfb8aa3b, v55
	v_mul_f32_e32 v63, 0xbfb8aa3b, v51
	v_exp_f32_e32 v56, v56
	v_exp_f32_e32 v57, v57
	v_exp_f32_e32 v58, v58
	v_exp_f32_e32 v59, v59
	v_exp_f32_e32 v60, v60
	v_exp_f32_e32 v61, v61
	v_exp_f32_e32 v62, v62
	v_exp_f32_e32 v63, v63
	v_add_f32_e32 v56, 1.0, v56
	v_add_f32_e32 v57, 1.0, v57
	v_add_f32_e32 v58, 1.0, v58
	v_add_f32_e32 v59, 1.0, v59
	v_add_f32_e32 v60, 1.0, v60
	v_add_f32_e32 v61, 1.0, v61
	v_add_f32_e32 v62, 1.0, v62
	v_add_f32_e32 v63, 1.0, v63
	v_rcp_f32_e32 v56, v56
	v_rcp_f32_e32 v57, v57
	v_rcp_f32_e32 v58, v58
	v_rcp_f32_e32 v59, v59
	v_rcp_f32_e32 v60, v60
	v_rcp_f32_e32 v61, v61
	v_rcp_f32_e32 v62, v62
	v_rcp_f32_e32 v63, v63
	v_mul_f32_e32 v52, v52, v56
	v_mul_f32_e32 v56, v48, v57
	v_mul_f32_e32 v48, v53, v58
	v_mul_f32_e32 v53, v49, v59
	v_mul_f32_e32 v49, v54, v60
	v_mul_f32_e32 v54, v50, v61
	v_mul_f32_e32 v50, v55, v62
	v_mul_f32_e32 v51, v51, v63
	v_cvt_pk_bf16_f32 v48, v52, v48
	v_cvt_pk_bf16_f32 v49, v49, v50
	v_cvt_pk_bf16_f32 v50, v56, v53
	v_cvt_pk_bf16_f32 v51, v54, v51
	s_and_saveexec_b64 s[14:15], vcc
	s_cbranch_execz .LBB0_404
	global_store_dwordx4 v[72:73], v[48:51], off offset:256
.LBB0_404:
	s_or_b64 exec, exec, s[14:15]
	s_nop 1
	v_lshlrev_b64 v[48:49], 9, v[152:153]
	v_lshl_add_u64 v[48:49], v[154:155], 0, v[48:49]
	s_mov_b64 s[14:15], 0x12000
	s_movk_i32 s2, 0x76c
	v_lshl_add_u64 v[48:49], v[48:49], 0, s[14:15]
	v_cmp_gt_i32_e32 vcc, s2, v152
	v_pk_add_f32 v[46:47], v[46:47], v[174:175]
	v_pk_add_f32 v[44:45], v[44:45], v[172:173]
	v_pk_add_f32 v[42:43], v[42:43], v[178:179]
	v_pk_add_f32 v[40:41], v[40:41], v[176:177]
	v_mul_f32_e32 v50, 0xbfb8aa3b, v44
	v_mul_f32_e32 v51, 0xbfb8aa3b, v40
	v_mul_f32_e32 v52, 0xbfb8aa3b, v45
	v_mul_f32_e32 v53, 0xbfb8aa3b, v41
	v_mul_f32_e32 v54, 0xbfb8aa3b, v46
	v_mul_f32_e32 v55, 0xbfb8aa3b, v42
	v_mul_f32_e32 v56, 0xbfb8aa3b, v47
	v_mul_f32_e32 v57, 0xbfb8aa3b, v43
	v_exp_f32_e32 v50, v50
	v_exp_f32_e32 v51, v51
	v_exp_f32_e32 v52, v52
	v_exp_f32_e32 v53, v53
	v_exp_f32_e32 v54, v54
	v_exp_f32_e32 v55, v55
	v_exp_f32_e32 v56, v56
	v_exp_f32_e32 v57, v57
	v_add_f32_e32 v50, 1.0, v50
	v_add_f32_e32 v51, 1.0, v51
	v_add_f32_e32 v52, 1.0, v52
	v_add_f32_e32 v53, 1.0, v53
	v_add_f32_e32 v54, 1.0, v54
	v_add_f32_e32 v55, 1.0, v55
	v_add_f32_e32 v56, 1.0, v56
	v_add_f32_e32 v57, 1.0, v57
	v_rcp_f32_e32 v50, v50
	v_rcp_f32_e32 v51, v51
	v_rcp_f32_e32 v52, v52
	v_rcp_f32_e32 v53, v53
	v_rcp_f32_e32 v54, v54
	v_rcp_f32_e32 v55, v55
	v_rcp_f32_e32 v56, v56
	v_rcp_f32_e32 v57, v57
	v_mul_f32_e32 v44, v44, v50
	v_mul_f32_e32 v50, v40, v51
	v_mul_f32_e32 v40, v45, v52
	v_mul_f32_e32 v45, v41, v53
	v_mul_f32_e32 v41, v46, v54
	v_mul_f32_e32 v46, v42, v55
	v_mul_f32_e32 v42, v47, v56
	v_mul_f32_e32 v43, v43, v57
	v_cvt_pk_bf16_f32 v40, v44, v40
	v_cvt_pk_bf16_f32 v41, v41, v42
	v_cvt_pk_bf16_f32 v42, v50, v45
	v_cvt_pk_bf16_f32 v43, v46, v43
	s_and_saveexec_b64 s[14:15], vcc
	s_cbranch_execz .LBB0_406
	global_store_dwordx4 v[48:49], v[40:43], off
.LBB0_406:
	s_or_b64 exec, exec, s[14:15]
	s_nop 1
	v_pk_add_f32 v[38:39], v[38:39], v[190:191]
	v_pk_add_f32 v[36:37], v[36:37], v[188:189]
	v_pk_add_f32 v[34:35], v[34:35], v[194:195]
	v_pk_add_f32 v[32:33], v[32:33], v[192:193]
	v_mul_f32_e32 v40, 0xbfb8aa3b, v36
	v_mul_f32_e32 v41, 0xbfb8aa3b, v32
	v_mul_f32_e32 v42, 0xbfb8aa3b, v37
	v_mul_f32_e32 v43, 0xbfb8aa3b, v33
	v_mul_f32_e32 v44, 0xbfb8aa3b, v38
	v_mul_f32_e32 v45, 0xbfb8aa3b, v34
	v_mul_f32_e32 v46, 0xbfb8aa3b, v39
	v_mul_f32_e32 v47, 0xbfb8aa3b, v35
	v_exp_f32_e32 v40, v40
	v_exp_f32_e32 v41, v41
	v_exp_f32_e32 v42, v42
	v_exp_f32_e32 v43, v43
	v_exp_f32_e32 v44, v44
	v_exp_f32_e32 v45, v45
	v_exp_f32_e32 v46, v46
	v_exp_f32_e32 v47, v47
	v_add_f32_e32 v40, 1.0, v40
	v_add_f32_e32 v41, 1.0, v41
	v_add_f32_e32 v42, 1.0, v42
	v_add_f32_e32 v43, 1.0, v43
	v_add_f32_e32 v44, 1.0, v44
	v_add_f32_e32 v45, 1.0, v45
	v_add_f32_e32 v46, 1.0, v46
	v_add_f32_e32 v47, 1.0, v47
	v_rcp_f32_e32 v40, v40
	v_rcp_f32_e32 v41, v41
	v_rcp_f32_e32 v42, v42
	v_rcp_f32_e32 v43, v43
	v_rcp_f32_e32 v44, v44
	v_rcp_f32_e32 v45, v45
	v_rcp_f32_e32 v46, v46
	v_rcp_f32_e32 v47, v47
	v_mul_f32_e32 v36, v36, v40
	v_mul_f32_e32 v40, v32, v41
	v_mul_f32_e32 v32, v37, v42
	v_mul_f32_e32 v37, v33, v43
	v_mul_f32_e32 v33, v38, v44
	v_mul_f32_e32 v38, v34, v45
	v_mul_f32_e32 v34, v39, v46
	v_mul_f32_e32 v35, v35, v47
	v_cvt_pk_bf16_f32 v32, v36, v32
	v_cvt_pk_bf16_f32 v33, v33, v34
	v_cvt_pk_bf16_f32 v34, v40, v37
	v_cvt_pk_bf16_f32 v35, v38, v35
	s_and_saveexec_b64 s[14:15], vcc
	s_cbranch_execz .LBB0_408
	global_store_dwordx4 v[48:49], v[32:35], off offset:256
; __device__ __forceinline__ unsigned cvt_pk_bf16(float lo, float hi) { unsigned r; asm volatile("v_cvt_pk_bf16_f32 %0, %1, %2" : "=v"(r) : "v"(lo), "v"(hi)); return r; }
; __device__ __forceinline__ float sigm(float x) { return __builtin_amdgcn_rcpf(1.0f + __builtin_amdgcn_exp2f(-1.4426950408889634f * x)); }
;     __device__ __forceinline__ void operator()(const f32x4 (&acc)[2][2][4][2], const Unit& u, int wr, int wc, int fr, int fq) const {
;     ...
;             for (int m = 0; m < 4; ++m) { const int row = row0 + ai * HALF + m * 16;
; #pragma unroll
;                 for (int bj = 0; bj < 2; ++bj) { const f32x4 b0 = *(const f32x4*)(bb + col0 + bj * HALF), b1 = *(const f32x4*)(bb + col0 + bj * HALF + 4);
;                     f32x4 v0 = acc[ai][bj][m][0] + b0, v1 = acc[ai][bj][m][1] + b1;
; #pragma unroll
;                     for (int e = 0; e < 4; ++e) { v0[e] = v0[e] * sigm(v0[e]); v1[e] = v1[e] * sigm(v1[e]); }
;                     u32x4 w; w.x = cvt_pk_bf16(v0[0], v0[1]); w.y = cvt_pk_bf16(v0[2], v0[3]); w.z = cvt_pk_bf16(v1[0], v1[1]); w.w = cvt_pk_bf16(v1[2], v1[3]);
;                     if (row < nvalid) *(u32x4*)(O + (size_t)row * 256 + col0 + bj * HALF) = w; } }
.LBB0_408:
	s_or_b64 exec, exec, s[14:15]
	s_nop 1
	v_lshlrev_b64 v[32:33], 9, v[152:153]
	v_lshl_add_u64 v[32:33], v[154:155], 0, v[32:33]
	s_mov_b64 s[14:15], 0x14000
	s_movk_i32 s2, 0x75c
	v_lshl_add_u64 v[32:33], v[32:33], 0, s[14:15]
	v_cmp_gt_i32_e32 vcc, s2, v152
	v_pk_add_f32 v[30:31], v[30:31], v[174:175]
	v_pk_add_f32 v[28:29], v[28:29], v[172:173]
	v_pk_add_f32 v[26:27], v[26:27], v[178:179]
	v_pk_add_f32 v[24:25], v[24:25], v[176:177]
	v_mul_f32_e32 v34, 0xbfb8aa3b, v28
	v_mul_f32_e32 v35, 0xbfb8aa3b, v24
	v_mul_f32_e32 v36, 0xbfb8aa3b, v29
	v_mul_f32_e32 v37, 0xbfb8aa3b, v25
	v_mul_f32_e32 v38, 0xbfb8aa3b, v30
	v_mul_f32_e32 v39, 0xbfb8aa3b, v26
	v_mul_f32_e32 v40, 0xbfb8aa3b, v31
	v_mul_f32_e32 v41, 0xbfb8aa3b, v27
	v_exp_f32_e32 v34, v34
	v_exp_f32_e32 v35, v35
	v_exp_f32_e32 v36, v36
	v_exp_f32_e32 v37, v37
	v_exp_f32_e32 v38, v38
	v_exp_f32_e32 v39, v39
	v_exp_f32_e32 v40, v40
	v_exp_f32_e32 v41, v41
	v_add_f32_e32 v34, 1.0, v34
	v_add_f32_e32 v35, 1.0, v35
	v_add_f32_e32 v36, 1.0, v36
	v_add_f32_e32 v37, 1.0, v37
	v_add_f32_e32 v38, 1.0, v38
	v_add_f32_e32 v39, 1.0, v39
	v_add_f32_e32 v40, 1.0, v40
	v_add_f32_e32 v41, 1.0, v41
	v_rcp_f32_e32 v34, v34
	v_rcp_f32_e32 v35, v35
	v_rcp_f32_e32 v36, v36
	v_rcp_f32_e32 v37, v37
	v_rcp_f32_e32 v38, v38
	v_rcp_f32_e32 v39, v39
	v_rcp_f32_e32 v40, v40
	v_rcp_f32_e32 v41, v41
	v_mul_f32_e32 v28, v28, v34
	v_mul_f32_e32 v34, v24, v35
	v_mul_f32_e32 v24, v29, v36
	v_mul_f32_e32 v29, v25, v37
	v_mul_f32_e32 v25, v30, v38
	v_mul_f32_e32 v30, v26, v39
	v_mul_f32_e32 v26, v31, v40
	v_mul_f32_e32 v27, v27, v41
	v_cvt_pk_bf16_f32 v24, v28, v24
	v_cvt_pk_bf16_f32 v25, v25, v26
	v_cvt_pk_bf16_f32 v26, v34, v29
	v_cvt_pk_bf16_f32 v27, v30, v27
	s_and_saveexec_b64 s[14:15], vcc
	s_cbranch_execz .LBB0_410
	global_store_dwordx4 v[32:33], v[24:27], off
.LBB0_410:
	s_or_b64 exec, exec, s[14:15]
	s_nop 1
	v_pk_add_f32 v[22:23], v[22:23], v[190:191]
	v_pk_add_f32 v[20:21], v[20:21], v[188:189]
	v_pk_add_f32 v[18:19], v[18:19], v[194:195]
	v_pk_add_f32 v[16:17], v[16:17], v[192:193]
	v_mul_f32_e32 v24, 0xbfb8aa3b, v20
	v_mul_f32_e32 v25, 0xbfb8aa3b, v16
	v_mul_f32_e32 v26, 0xbfb8aa3b, v21
	v_mul_f32_e32 v27, 0xbfb8aa3b, v17
	v_mul_f32_e32 v28, 0xbfb8aa3b, v22
	v_mul_f32_e32 v29, 0xbfb8aa3b, v18
	v_mul_f32_e32 v30, 0xbfb8aa3b, v23
	v_mul_f32_e32 v31, 0xbfb8aa3b, v19
	v_exp_f32_e32 v24, v24
	v_exp_f32_e32 v25, v25
	v_exp_f32_e32 v26, v26
	v_exp_f32_e32 v27, v27
	v_exp_f32_e32 v28, v28
	v_exp_f32_e32 v29, v29
	v_exp_f32_e32 v30, v30
	v_exp_f32_e32 v31, v31
	v_add_f32_e32 v24, 1.0, v24
	v_add_f32_e32 v25, 1.0, v25
	v_add_f32_e32 v26, 1.0, v26
	v_add_f32_e32 v27, 1.0, v27
	v_add_f32_e32 v28, 1.0, v28
	v_add_f32_e32 v29, 1.0, v29
	v_add_f32_e32 v30, 1.0, v30
	v_add_f32_e32 v31, 1.0, v31
	v_rcp_f32_e32 v24, v24
	v_rcp_f32_e32 v25, v25
	v_rcp_f32_e32 v26, v26
	v_rcp_f32_e32 v27, v27
	v_rcp_f32_e32 v28, v28
	v_rcp_f32_e32 v29, v29
	v_rcp_f32_e32 v30, v30
	v_rcp_f32_e32 v31, v31
	v_mul_f32_e32 v20, v20, v24
	v_mul_f32_e32 v24, v16, v25
	v_mul_f32_e32 v16, v21, v26
	v_mul_f32_e32 v21, v17, v27
	v_mul_f32_e32 v17, v22, v28
	v_mul_f32_e32 v22, v18, v29
	v_mul_f32_e32 v18, v23, v30
	v_mul_f32_e32 v19, v19, v31
	v_cvt_pk_bf16_f32 v16, v20, v16
	v_cvt_pk_bf16_f32 v17, v17, v18
	v_cvt_pk_bf16_f32 v18, v24, v21
	v_cvt_pk_bf16_f32 v19, v22, v19
	s_and_saveexec_b64 s[14:15], vcc
	s_cbranch_execz .LBB0_412
	global_store_dwordx4 v[32:33], v[16:19], off offset:256
.LBB0_412:
	s_or_b64 exec, exec, s[14:15]
	s_nop 1
	v_lshlrev_b64 v[16:17], 9, v[152:153]
	v_lshl_add_u64 v[16:17], v[154:155], 0, v[16:17]
	s_mov_b64 s[14:15], 0x16000
	s_movk_i32 s2, 0x74c
	v_lshl_add_u64 v[16:17], v[16:17], 0, s[14:15]
	v_cmp_gt_i32_e32 vcc, s2, v152
	v_pk_add_f32 v[8:9], v[8:9], v[176:177]
	v_pk_add_f32 v[12:13], v[12:13], v[172:173]
	v_pk_add_f32 v[14:15], v[14:15], v[174:175]
	v_mul_f32_e32 v18, 0xbfb8aa3b, v12
	v_exp_f32_e32 v18, v18
	v_pk_add_f32 v[10:11], v[10:11], v[178:179]
	v_add_f32_e32 v18, 1.0, v18
	v_rcp_f32_e32 v18, v18
	s_nop 0
	v_mul_f32_e32 v12, v12, v18
	v_mul_f32_e32 v18, 0xbfb8aa3b, v8
	v_exp_f32_e32 v18, v18
	s_nop 0
	v_add_f32_e32 v18, 1.0, v18
	v_rcp_f32_e32 v18, v18
	s_nop 0
	v_mul_f32_e32 v18, v8, v18
	v_mul_f32_e32 v8, 0xbfb8aa3b, v13
	v_exp_f32_e32 v8, v8
	s_nop 0
	v_add_f32_e32 v8, 1.0, v8
	v_rcp_f32_e32 v8, v8
	s_nop 0
	v_mul_f32_e32 v8, v13, v8
	v_mul_f32_e32 v13, 0xbfb8aa3b, v9
	v_exp_f32_e32 v13, v13
	v_cvt_pk_bf16_f32 v8, v12, v8
	s_nop 0
	v_add_f32_e32 v13, 1.0, v13
	v_rcp_f32_e32 v13, v13
	s_nop 0
	v_mul_f32_e32 v13, v9, v13
	v_mul_f32_e32 v9, 0xbfb8aa3b, v14
	v_exp_f32_e32 v9, v9
	s_nop 0
	v_add_f32_e32 v9, 1.0, v9
	v_rcp_f32_e32 v9, v9
	s_nop 0
	v_mul_f32_e32 v9, v14, v9
	v_mul_f32_e32 v14, 0xbfb8aa3b, v10
	v_exp_f32_e32 v14, v14
	s_nop 0
	v_add_f32_e32 v14, 1.0, v14
	v_rcp_f32_e32 v14, v14
	s_nop 0
	v_mul_f32_e32 v14, v10, v14
	v_mul_f32_e32 v10, 0xbfb8aa3b, v15
	v_exp_f32_e32 v10, v10
	s_nop 0
	v_add_f32_e32 v10, 1.0, v10
	v_rcp_f32_e32 v10, v10
	s_nop 0
	v_mul_f32_e32 v10, v15, v10
	v_mul_f32_e32 v15, 0xbfb8aa3b, v11
	v_exp_f32_e32 v15, v15
	v_cvt_pk_bf16_f32 v9, v9, v10
	v_cvt_pk_bf16_f32 v10, v18, v13
	s_nop 0
	v_add_f32_e32 v15, 1.0, v15
	v_rcp_f32_e32 v15, v15
	s_nop 0
	v_mul_f32_e32 v11, v11, v15
	v_cvt_pk_bf16_f32 v11, v14, v11
	s_and_saveexec_b64 s[14:15], vcc
	s_cbranch_execz .LBB0_414
	global_store_dwordx4 v[16:17], v[8:11], off
.LBB0_414:
	s_or_b64 exec, exec, s[14:15]
	s_nop 1
	v_pk_add_f32 v[6:7], v[6:7], v[190:191]
	v_pk_add_f32 v[4:5], v[4:5], v[188:189]
	v_pk_add_f32 v[2:3], v[2:3], v[194:195]
	v_pk_add_f32 v[0:1], v[0:1], v[192:193]
	v_mul_f32_e32 v8, 0xbfb8aa3b, v4
	v_mul_f32_e32 v9, 0xbfb8aa3b, v0
	v_mul_f32_e32 v10, 0xbfb8aa3b, v5
	v_mul_f32_e32 v11, 0xbfb8aa3b, v1
	v_mul_f32_e32 v12, 0xbfb8aa3b, v6
	v_mul_f32_e32 v13, 0xbfb8aa3b, v2
	v_mul_f32_e32 v14, 0xbfb8aa3b, v7
	v_mul_f32_e32 v15, 0xbfb8aa3b, v3
	v_exp_f32_e32 v8, v8
	v_exp_f32_e32 v9, v9
	v_exp_f32_e32 v10, v10
	v_exp_f32_e32 v11, v11
	v_exp_f32_e32 v12, v12
	v_exp_f32_e32 v13, v13
	v_exp_f32_e32 v14, v14
	v_exp_f32_e32 v15, v15
	v_add_f32_e32 v8, 1.0, v8
	v_add_f32_e32 v9, 1.0, v9
	v_add_f32_e32 v10, 1.0, v10
	v_add_f32_e32 v11, 1.0, v11
	v_add_f32_e32 v12, 1.0, v12
	v_add_f32_e32 v13, 1.0, v13
	v_add_f32_e32 v14, 1.0, v14
	v_add_f32_e32 v15, 1.0, v15
	v_rcp_f32_e32 v8, v8
	v_rcp_f32_e32 v9, v9
	v_rcp_f32_e32 v10, v10
	v_rcp_f32_e32 v11, v11
	v_rcp_f32_e32 v12, v12
	v_rcp_f32_e32 v13, v13
	v_rcp_f32_e32 v14, v14
	v_rcp_f32_e32 v15, v15
	v_mul_f32_e32 v4, v4, v8
	v_mul_f32_e32 v8, v0, v9
	v_mul_f32_e32 v0, v5, v10
	v_mul_f32_e32 v5, v1, v11
	v_mul_f32_e32 v1, v6, v12
	v_mul_f32_e32 v6, v2, v13
	v_mul_f32_e32 v2, v7, v14
	v_mul_f32_e32 v3, v3, v15
	v_cvt_pk_bf16_f32 v0, v4, v0
	v_cvt_pk_bf16_f32 v1, v1, v2
	v_cvt_pk_bf16_f32 v2, v8, v5
	v_cvt_pk_bf16_f32 v3, v6, v3
	s_and_saveexec_b64 s[14:15], vcc
	s_cbranch_execz .LBB0_416
	global_store_dwordx4 v[16:17], v[0:3], off offset:256
